# wt1 + P3 column-tile type permutation (2<->4, 3<->12): the six-unit workgroups get the cheap raw-copy epilogues instead of forget-gate and rope tiles
# speedup vs baseline: 1.0041x; 1.0012x over previous
.LBB0_777:
	s_or_b64 exec, exec, s[0:1]
	v_mov_b32_e32 v9, v0
	v_cndmask_b32_e64 v1, 0, 1, s[20:21]
	s_waitcnt lgkmcnt(0)
	s_barrier
	v_cmp_ne_u32_e64 s[0:1], 1, v1
	s_andn2_b64 vcc, exec, s[20:21]
	v_readfirstlane_b32 s4, v9
	s_cbranch_vccnz .LBB0_779
	s_lshr_b32 s5, s30, 29
	s_add_i32 s5, s2, s5
	s_ashr_i32 s6, s5, 3
	s_and_b32 s5, s5, -8
	s_sub_i32 s5, s2, s5
	s_cmp_lt_i32 s5, 0
	s_movk_i32 s7, 0xa9
	s_cselect_b32 s7, s7, 0xa8
	s_mul_i32 s5, s5, s7
	s_add_i32 s5, s5, s6
	s_mul_hi_i32 s6, s5, 0x30c30c31
	s_lshr_b32 s7, s6, 31
	s_ashr_i32 s6, s6, 5
	s_add_i32 s6, s6, s7
	s_lshl_b32 s7, s6, 3
	s_mulk_i32 s6, 0xa8
	s_sub_i32 s5, s5, s6
	s_sext_i32_i16 s6, s5
	s_bfe_u32 s6, s6, 0x3001c
	s_add_i32 s6, s5, s6
	s_sext_i32_i16 s8, s6
	s_and_b32 s6, s6, 0xfff8
	s_sub_i32 s5, s5, s6
	s_sext_i32_i16 s5, s5
	s_add_i32 s6, s7, s5
	s_ashr_i32 s76, s8, 3
	s_mov_b32 s32, s76
	s_cmp_eq_u32 s76, 2
	s_cselect_b32 s32, 4, s32
	s_cmp_eq_u32 s76, 4
	s_cselect_b32 s32, 2, s32
	s_cmp_eq_u32 s76, 3
	s_cselect_b32 s32, 12, s32
	s_cmp_eq_u32 s76, 12
	s_cselect_b32 s32, 3, s32
	s_mov_b32 s76, s32

.LBB0_787:
	v_add_u32_e32 v202, 0, v205
	v_add_u32_e32 v236, 0x10000, v202
	v_add_u32_e32 v237, 0x14000, v202
	ds_read_b128 v[146:149], v236
	ds_read_b128 v[150:153], v236 offset:1024
	ds_read_b128 v[154:157], v236 offset:2048
	ds_read_b128 v[158:161], v236 offset:3072
	ds_read_b128 v[130:133], v237
	ds_read_b128 v[134:137], v237 offset:1024
	ds_read_b128 v[138:141], v237 offset:2048
	ds_read_b128 v[142:145], v237 offset:3072
	s_add_i32 s42, s42, 1
	v_lshl_add_u64 v[220:221], s[78:79], 0, v[194:195]
	s_add_i32 s0, s77, 0x8000
	v_lshl_add_u64 v[222:223], v[220:221], 0, s[36:37]
	s_mov_b32 m0, s0
	s_add_i32 s7, s77, 0xa000
	ds_read_b128 v[186:189], v235
	ds_read_b128 v[190:193], v235 offset:1024
	ds_read_b128 v[178:181], v235 offset:2048
	ds_read_b128 v[182:185], v235 offset:3072
	ds_read_b128 v[170:173], v235 offset:4096
	ds_read_b128 v[174:177], v235 offset:5120
	ds_read_b128 v[162:165], v235 offset:6144
	ds_read_b128 v[166:169], v235 offset:7168
	global_load_lds_dwordx4 v[222:223], off
	v_lshl_add_u64 v[222:223], s[78:79], 0, v[198:199]
	s_add_u32 s4, s78, 0x40080
	v_lshl_add_u64 v[224:225], v[222:223], 0, s[36:37]
	s_mov_b32 m0, s7
	s_addc_u32 s5, s79, 0
	s_add_i32 s57, s77, 0xc000
	global_load_lds_dwordx4 v[224:225], off
	v_lshl_add_u64 v[224:225], s[4:5], 0, v[194:195]
	s_mov_b32 m0, s57
	s_add_i32 s58, s77, 0xe000
	global_load_lds_dwordx4 v[224:225], off
	v_lshl_add_u64 v[224:225], s[4:5], 0, v[198:199]
	s_mov_b32 m0, s58
	s_nop 0
	global_load_lds_dwordx4 v[224:225], off
	s_mul_i32 s4, s42, s43
	s_mul_hi_u32 s5, s42, s3
	s_add_i32 s5, s5, s4
	s_mul_i32 s4, s42, s3
	s_add_u32 s28, s4, s2
	s_addc_u32 s29, s5, s30
	v_cmp_gt_i64_e32 vcc, s[28:29], v[218:219]
	v_cmp_lt_i64_e64 s[4:5], s[28:29], v[216:217]
	s_cbranch_vccnz .LBB0_789
	s_ashr_i32 s12, s28, 31
	s_lshr_b32 s12, s12, 29
	s_add_i32 s12, s28, s12
	s_ashr_i32 s16, s12, 3
	s_and_b32 s12, s12, -8
	s_sub_i32 s12, s28, s12
	s_cmp_lt_i32 s12, 0
	s_movk_i32 s17, 0xa9
	s_cselect_b32 s17, s17, 0xa8
	s_mul_i32 s12, s12, s17
	s_add_i32 s12, s12, s16
	s_mul_hi_i32 s16, s12, 0x30c30c31
	s_lshr_b32 s17, s16, 31
	s_ashr_i32 s16, s16, 5
	s_add_i32 s16, s16, s17
	s_lshl_b32 s17, s16, 3
	s_mulk_i32 s16, 0xa8
	s_sub_i32 s12, s12, s16
	s_bfe_u32 s16, s12, 0x3001c
	s_add_i32 s16, s12, s16
	s_sext_i32_i16 s18, s16
	s_and_b32 s16, s16, 0xfff8
	s_sub_i32 s12, s12, s16
	s_sext_i32_i16 s12, s12
	s_add_i32 s72, s17, s12
	s_ashr_i32 s74, s18, 3
	s_mov_b32 s32, s74
	s_cmp_eq_u32 s74, 2
	s_cselect_b32 s32, 4, s32
	s_cmp_eq_u32 s74, 4
	s_cselect_b32 s32, 2, s32
	s_cmp_eq_u32 s74, 3
	s_cselect_b32 s32, 12, s32
	s_cmp_eq_u32 s74, 12
	s_cselect_b32 s32, 3, s32
	s_mov_b32 s74, s32
	s_mov_b32 s12, s42
